# v28 + L2 prefetch of the next phase's weight panel (first two K-tiles) issued by one wave while the workgroup sits in the seam
# speedup vs baseline: 1.0052x; 1.0010x over previous
; __device__ __forceinline__ void xcd_barrier(const XcdBarrier& b, int tid) {
;     asm volatile("s_waitcnt vmcnt(0)" ::: "memory");
;     __syncthreads();
;     if (tid == 0) {
;         unsigned* bar = b.bar;
;         __builtin_amdgcn_s_waitcnt(0);
;         unsigned nloc = b.st[0], nx = b.st[1];
;         if (nloc == 0u) { xcd_barrier_complete(bar, b.x, nloc, nx); b.st[0] = nloc; b.st[1] = nx; }
.LBB0_383:
	s_cmp_gt_i32 s43, 2
	s_cselect_b64 s[2:3], -1, 0
	s_and_b64 s[0:1], s[4:5], s[2:3]
	s_andn2_b64 vcc, exec, s[0:1]
	s_cbranch_vccnz .LBB0_437
	s_getreg_b32 s0, hwreg(HW_REG_XCC_ID, 0, 4)
	v_mbcnt_hi_u32_b32 v0, -1, v230
	s_waitcnt vmcnt(0)
	v_sub_u32_e32 v0, 0, v0
	v_readlane_b32 s1, v248, 0
	s_waitcnt vmcnt(0) lgkmcnt(0)
	s_barrier
	v_readlane_b32 s98, v248, 0
	s_nop 3
	s_cmp_eq_u32 s98, 64
	s_cbranch_scc0 .Lwpf_done_1
	v_mbcnt_hi_u32_b32 v1, -1, v230
	s_add_u32 s98, s40, 0xc00000
	s_addc_u32 s99, s41, 0
	s_lshr_b32 s100, s33, 3
	s_mul_i32 s100, s100, 32
	v_mov_b32_e32 v2, v1
	v_min_u32_e32 v2, 63, v2
	v_lshrrev_b32_e32 v3, 1, v2
	v_add_u32_e32 v3, s100, v3
	v_mul_u32_u24_e32 v3, 0x1600, v3
	v_and_b32_e32 v4, 1, v2
	v_lshl_add_u32 v3, v4, 7, v3
	global_load_dword v239, v3, s[98:99]
.Lwpf_done_1:
	v_cmp_eq_u32_e32 vcc, s1, v0
	s_and_saveexec_b64 s[4:5], vcc
	s_cbranch_execz .LBB0_436
	s_add_i32 s1, 0, 0x20000
	v_mov_b32_e32 v0, s1
	s_waitcnt vmcnt(0) expcnt(0) lgkmcnt(0)
	ds_read_b32 v2, v0
	s_add_i32 s1, 0, 0x20004
	v_mov_b32_e32 v0, s1
	ds_read_b32 v0, v0
	s_and_b32 s0, s0, 15
	s_waitcnt lgkmcnt(1)
	v_cmp_ne_u32_e32 vcc, 0, v2
	s_cbranch_vccnz .LBB0_400
	s_add_u32 s6, s40, 0x1000
	s_addc_u32 s7, s41, 0
	s_add_u32 s8, s40, 0x1100
	s_addc_u32 s9, s41, 0
	s_add_u32 s10, s40, 0x1200
	s_addc_u32 s11, s41, 0
	s_add_u32 s12, s40, 0x1300
	s_addc_u32 s13, s41, 0
	s_mov_b32 s1, 1
	v_mov_b32_e32 v16, 0
	s_branch .LBB0_388

; __device__ __forceinline__ void xcd_barrier(const XcdBarrier& b, int tid) {
;     asm volatile("s_waitcnt vmcnt(0)" ::: "memory");
;     __syncthreads();
;     if (tid == 0) {
;         unsigned* bar = b.bar;
;         __builtin_amdgcn_s_waitcnt(0);
;         unsigned nloc = b.st[0], nx = b.st[1];
;         if (nloc == 0u) { xcd_barrier_complete(bar, b.x, nloc, nx); b.st[0] = nloc; b.st[1] = nx; }
.LBB0_492:
	s_cmp_gt_i32 s43, 3
	s_cselect_b64 s[2:3], -1, 0
	s_and_b64 s[0:1], s[8:9], s[2:3]
	s_andn2_b64 vcc, exec, s[0:1]
	s_cbranch_vccnz .LBB0_546
	s_getreg_b32 s0, hwreg(HW_REG_XCC_ID, 0, 4)
	v_mbcnt_hi_u32_b32 v0, -1, v230
	s_waitcnt vmcnt(0)
	v_sub_u32_e32 v0, 0, v0
	v_readlane_b32 s1, v248, 0
	s_waitcnt vmcnt(0) lgkmcnt(0)
	s_barrier
	v_readlane_b32 s98, v248, 0
	s_nop 3
	s_cmp_eq_u32 s98, 64
	s_cbranch_scc0 .Lwpf_done_2
	v_mbcnt_hi_u32_b32 v1, -1, v230
	s_add_u32 s98, s40, 0x1200000
	s_addc_u32 s99, s41, 0
	s_lshr_b32 s100, s33, 3
	s_mul_i32 s100, s100, 160
	v_mov_b32_e32 v2, v1
	v_min_u32_e32 v2, 319, v2
	v_lshrrev_b32_e32 v3, 1, v2
	v_add_u32_e32 v3, s100, v3
	v_mul_u32_u24_e32 v3, 0x800, v3
	v_and_b32_e32 v4, 1, v2
	v_lshl_add_u32 v3, v4, 7, v3
	global_load_dword v240, v3, s[98:99]
	v_add_u32_e32 v2, 64, v1
	v_min_u32_e32 v2, 319, v2
	v_lshrrev_b32_e32 v3, 1, v2
	v_add_u32_e32 v3, s100, v3
	v_mul_u32_u24_e32 v3, 0x800, v3
	v_and_b32_e32 v4, 1, v2
	v_lshl_add_u32 v3, v4, 7, v3
	global_load_dword v240, v3, s[98:99]
	v_add_u32_e32 v2, 128, v1
	v_min_u32_e32 v2, 319, v2
	v_lshrrev_b32_e32 v3, 1, v2
	v_add_u32_e32 v3, s100, v3
	v_mul_u32_u24_e32 v3, 0x800, v3
	v_and_b32_e32 v4, 1, v2
	v_lshl_add_u32 v3, v4, 7, v3
	global_load_dword v240, v3, s[98:99]
	v_add_u32_e32 v2, 192, v1
	v_min_u32_e32 v2, 319, v2
	v_lshrrev_b32_e32 v3, 1, v2
	v_add_u32_e32 v3, s100, v3
	v_mul_u32_u24_e32 v3, 0x800, v3
	v_and_b32_e32 v4, 1, v2
	v_lshl_add_u32 v3, v4, 7, v3
	global_load_dword v240, v3, s[98:99]
	v_add_u32_e32 v2, 256, v1
	v_min_u32_e32 v2, 319, v2
	v_lshrrev_b32_e32 v3, 1, v2
	v_add_u32_e32 v3, s100, v3
	v_mul_u32_u24_e32 v3, 0x800, v3
	v_and_b32_e32 v4, 1, v2
	v_lshl_add_u32 v3, v4, 7, v3
	global_load_dword v240, v3, s[98:99]

; __device__ __forceinline__ void xcd_barrier(const XcdBarrier& b, int tid) {
;     asm volatile("s_waitcnt vmcnt(0)" ::: "memory");
;     __syncthreads();
;     if (tid == 0) {
;         unsigned* bar = b.bar;
;         __builtin_amdgcn_s_waitcnt(0);
;         unsigned nloc = b.st[0], nx = b.st[1];
;         if (nloc == 0u) { xcd_barrier_complete(bar, b.x, nloc, nx); b.st[0] = nloc; b.st[1] = nx; }
.LBB0_990:
	s_cmp_gt_u32 s43, 5
	v_readlane_b32 s2, v248, 3
	s_cselect_b64 s[0:1], -1, 0
	v_readlane_b32 s3, v248, 4
	s_and_b64 s[0:1], s[2:3], s[0:1]
	s_andn2_b64 vcc, exec, s[0:1]
	s_cbranch_vccnz .LBB0_1044
	s_getreg_b32 s0, hwreg(HW_REG_XCC_ID, 0, 4)
	v_mbcnt_hi_u32_b32 v0, -1, v230
	s_waitcnt vmcnt(0)
	v_sub_u32_e32 v0, 0, v0
	v_readlane_b32 s1, v248, 0
	s_waitcnt vmcnt(0) lgkmcnt(0)
	s_barrier
	v_readlane_b32 s98, v248, 0
	s_nop 3
	s_cmp_eq_u32 s98, 64
	s_cbranch_scc0 .Lwpf_done_4
	v_mbcnt_hi_u32_b32 v1, -1, v230
	s_add_u32 s98, s40, 0x1c00000
	s_addc_u32 s99, s41, 0
	s_lshr_b32 s100, s33, 3
	s_mul_i32 s100, s100, 32
	v_mov_b32_e32 v2, v1
	v_min_u32_e32 v2, 63, v2
	v_lshrrev_b32_e32 v3, 1, v2
	v_add_u32_e32 v3, s100, v3
	v_mul_u32_u24_e32 v3, 0x800, v3
	v_and_b32_e32 v4, 1, v2
	v_lshl_add_u32 v3, v4, 7, v3
	global_load_dword v240, v3, s[98:99]
.Lwpf_done_4:
	v_cmp_eq_u32_e32 vcc, s1, v0
	s_and_saveexec_b64 s[2:3], vcc
	s_cbranch_execz .LBB0_1043
	s_add_i32 s1, 0, 0x20000
	v_mov_b32_e32 v0, s1
	s_waitcnt vmcnt(0) expcnt(0) lgkmcnt(0)
	ds_read_b32 v2, v0
	s_add_i32 s1, 0, 0x20004
	v_mov_b32_e32 v0, s1
	ds_read_b32 v0, v0
	s_and_b32 s0, s0, 15
	s_waitcnt lgkmcnt(1)
	v_cmp_ne_u32_e32 vcc, 0, v2
	s_cbranch_vccnz .LBB0_1007
	s_add_u32 s4, s40, 0x1000
	s_addc_u32 s5, s41, 0
	s_add_u32 s6, s40, 0x1100
	s_addc_u32 s7, s41, 0
	s_add_u32 s8, s40, 0x1200
	s_addc_u32 s9, s41, 0
	s_add_u32 s10, s40, 0x1300
	s_addc_u32 s11, s41, 0
	s_mov_b32 s1, 1
	v_mov_b32_e32 v16, 0
	s_branch .LBB0_995

; __device__ __forceinline__ void xcd_barrier(const XcdBarrier& b, int tid) {
;     asm volatile("s_waitcnt vmcnt(0)" ::: "memory");
;     __syncthreads();
;     if (tid == 0) {
;         unsigned* bar = b.bar;
;         __builtin_amdgcn_s_waitcnt(0);
;         unsigned nloc = b.st[0], nx = b.st[1];
;         if (nloc == 0u) { xcd_barrier_complete(bar, b.x, nloc, nx); b.st[0] = nloc; b.st[1] = nx; }
.LBB0_1074:
	s_cmp_gt_i32 s43, 8
	s_cselect_b64 s[2:3], -1, 0
	s_and_b64 s[0:1], s[4:5], s[2:3]
	s_andn2_b64 vcc, exec, s[0:1]
	s_cbranch_vccnz .LBB0_1128
	s_getreg_b32 s0, hwreg(HW_REG_XCC_ID, 0, 4)
	v_mbcnt_hi_u32_b32 v0, -1, v230
	s_waitcnt vmcnt(0)
	v_sub_u32_e32 v0, 0, v0
	v_readlane_b32 s1, v248, 0
	s_waitcnt vmcnt(0) lgkmcnt(0)
	s_barrier
	v_readlane_b32 s98, v248, 0
	s_nop 3
	s_cmp_eq_u32 s98, 64
	s_cbranch_scc0 .Lwpf_done_5
	v_mbcnt_hi_u32_b32 v1, -1, v230
	s_add_u32 s98, s40, 0x1e00000
	s_addc_u32 s99, s41, 0
	s_lshr_b32 s100, s33, 3
	s_mul_i32 s100, s100, 32
	v_mov_b32_e32 v2, v1
	v_min_u32_e32 v2, 63, v2
	v_lshrrev_b32_e32 v3, 1, v2
	v_add_u32_e32 v3, s100, v3
	v_mul_u32_u24_e32 v3, 0x800, v3
	v_and_b32_e32 v4, 1, v2
	v_lshl_add_u32 v3, v4, 7, v3
	global_load_dword v240, v3, s[98:99]

; __device__ __forceinline__ void xcd_barrier(const XcdBarrier& b, int tid) {
;     asm volatile("s_waitcnt vmcnt(0)" ::: "memory");
;     __syncthreads();
;     if (tid == 0) {
;         unsigned* bar = b.bar;
;         __builtin_amdgcn_s_waitcnt(0);
;         unsigned nloc = b.st[0], nx = b.st[1];
;         if (nloc == 0u) { xcd_barrier_complete(bar, b.x, nloc, nx); b.st[0] = nloc; b.st[1] = nx; }
.LBB0_1171:
	s_cmp_gt_i32 s43, 9
	s_cselect_b64 s[2:3], -1, 0
	s_and_b64 s[0:1], s[6:7], s[2:3]
	s_andn2_b64 vcc, exec, s[0:1]
	s_cbranch_vccnz .LBB0_1225
	s_getreg_b32 s0, hwreg(HW_REG_XCC_ID, 0, 4)
	v_mbcnt_hi_u32_b32 v0, -1, v230
	s_waitcnt vmcnt(0)
	v_sub_u32_e32 v0, 0, v0
	v_readlane_b32 s1, v248, 0
	s_waitcnt vmcnt(0) lgkmcnt(0)
	s_barrier
	v_readlane_b32 s98, v248, 0
	s_nop 3
	s_cmp_eq_u32 s98, 64
	s_cbranch_scc0 .Lwpf_done_6
	v_mbcnt_hi_u32_b32 v1, -1, v230
	s_add_u32 s98, s40, 0x2000000
	s_addc_u32 s99, s41, 0
	s_lshr_b32 s100, s33, 3
	s_mul_i32 s100, s100, 176
	v_mov_b32_e32 v2, v1
	v_min_u32_e32 v2, 351, v2
	v_lshrrev_b32_e32 v3, 1, v2
	v_add_u32_e32 v3, s100, v3
	v_mul_u32_u24_e32 v3, 0x800, v3
	v_and_b32_e32 v4, 1, v2
	v_lshl_add_u32 v3, v4, 7, v3
	global_load_dword v240, v3, s[98:99]
	v_add_u32_e32 v2, 64, v1
	v_min_u32_e32 v2, 351, v2
	v_lshrrev_b32_e32 v3, 1, v2
	v_add_u32_e32 v3, s100, v3
	v_mul_u32_u24_e32 v3, 0x800, v3
	v_and_b32_e32 v4, 1, v2
	v_lshl_add_u32 v3, v4, 7, v3
	global_load_dword v240, v3, s[98:99]
	v_add_u32_e32 v2, 128, v1
	v_min_u32_e32 v2, 351, v2
	v_lshrrev_b32_e32 v3, 1, v2
	v_add_u32_e32 v3, s100, v3
	v_mul_u32_u24_e32 v3, 0x800, v3
	v_and_b32_e32 v4, 1, v2
	v_lshl_add_u32 v3, v4, 7, v3
	global_load_dword v240, v3, s[98:99]
	v_add_u32_e32 v2, 192, v1
	v_min_u32_e32 v2, 351, v2
	v_lshrrev_b32_e32 v3, 1, v2
	v_add_u32_e32 v3, s100, v3
	v_mul_u32_u24_e32 v3, 0x800, v3
	v_and_b32_e32 v4, 1, v2
	v_lshl_add_u32 v3, v4, 7, v3
	global_load_dword v240, v3, s[98:99]
	v_add_u32_e32 v2, 256, v1
	v_min_u32_e32 v2, 351, v2
	v_lshrrev_b32_e32 v3, 1, v2
	v_add_u32_e32 v3, s100, v3
	v_mul_u32_u24_e32 v3, 0x800, v3
	v_and_b32_e32 v4, 1, v2
	v_lshl_add_u32 v3, v4, 7, v3
	global_load_dword v240, v3, s[98:99]
	v_add_u32_e32 v2, 320, v1
	v_min_u32_e32 v2, 351, v2
	v_lshrrev_b32_e32 v3, 1, v2
	v_add_u32_e32 v3, s100, v3
	v_mul_u32_u24_e32 v3, 0x800, v3
	v_and_b32_e32 v4, 1, v2
	v_lshl_add_u32 v3, v4, 7, v3
	global_load_dword v240, v3, s[98:99]

; __device__ __forceinline__ void xcd_barrier(const XcdBarrier& b, int tid) {
;     asm volatile("s_waitcnt vmcnt(0)" ::: "memory");
;     __syncthreads();
;     if (tid == 0) {
;         unsigned* bar = b.bar;
;         __builtin_amdgcn_s_waitcnt(0);
;         unsigned nloc = b.st[0], nx = b.st[1];
;         if (nloc == 0u) { xcd_barrier_complete(bar, b.x, nloc, nx); b.st[0] = nloc; b.st[1] = nx; }
.LBB0_1245:
	s_cmp_gt_i32 s43, 10
	s_cselect_b64 s[2:3], -1, 0
	s_and_b64 s[0:1], s[4:5], s[2:3]
	s_andn2_b64 vcc, exec, s[0:1]
	s_cbranch_vccnz .LBB0_1299
	s_getreg_b32 s0, hwreg(HW_REG_XCC_ID, 0, 4)
	v_mbcnt_hi_u32_b32 v0, -1, v230
	s_waitcnt vmcnt(0)
	v_sub_u32_e32 v0, 0, v0
	v_readlane_b32 s1, v248, 0
	s_waitcnt vmcnt(0) lgkmcnt(0)
	s_barrier
	v_readlane_b32 s98, v248, 0
	s_nop 3
	s_cmp_eq_u32 s98, 64
	s_cbranch_scc0 .Lwpf_done_7
	v_mbcnt_hi_u32_b32 v1, -1, v230
	s_add_u32 s98, s40, 0x2b00000
	s_addc_u32 s99, s41, 0
	s_lshr_b32 s100, s33, 3
	s_mul_i32 s100, s100, 32
	v_mov_b32_e32 v2, v1
	v_min_u32_e32 v2, 63, v2
	v_lshrrev_b32_e32 v3, 1, v2
	v_add_u32_e32 v3, s100, v3
	v_mul_u32_u24_e32 v3, 0x1600, v3
	v_and_b32_e32 v4, 1, v2
	v_lshl_add_u32 v3, v4, 7, v3
	global_load_dword v240, v3, s[98:99]
